# grid barrier: the second-to-last arriver of each XCD starts an early L2 write-back so the XCD-last's write-back has little left to flush
# speedup vs baseline: 1.0051x; 1.0051x over previous
; __device__ __forceinline__ unsigned xb_add(unsigned* p, unsigned v) { return __hip_atomic_fetch_add(p, v, __ATOMIC_RELAXED, __HIP_MEMORY_SCOPE_AGENT); }
; __device__ __forceinline__ void xcd_barrier(const XcdBarrier& b) {
;     ...
;         const unsigned old = xb_add(&bar[XB_XSUB(b.x)], 1u);
;         const unsigned gen = old / nloc;
;         if (old + 1u == (gen + 1u) * nloc) {
;             __builtin_amdgcn_fence(__ATOMIC_RELEASE, "agent");
;             asm volatile("s_waitcnt vmcnt(0)" ::: "memory");
;             const unsigned og = xb_add(&bar[XB_TOP], 1u);
.Lxb0_hint:
	v_add_u32_e32 v8, 1, v6
	v_cmp_eq_u32_e32 vcc, v8, v4
	s_cbranch_vccz .Lxb0_early
	buffer_wbl2 sc1
